# baseline (speedup 1.0000x reference)
; #define WAIT_V(n) asm volatile("s_waitcnt vmcnt(" #n ")" ::: "memory")
; #define BAR __builtin_amdgcn_s_barrier()
; template <int MODE>
; __device__ __forceinline__ void gemm_tile(const int ph, const int which, const int pm, const int pn) {
;     ...
;   STAGE(SB(0, 0), RB, bcol, 0);
;   STAGE(SA(0, 0), RA, brow, 0);
;   STAGE(SB(0, 1), RB, bcolB, 0);
;   STAGE(SA(0, 1), RA, brow + HALF, 0);
;   if (wr == 1) BAR;
;   WAIT_V(4);
;   BAR;
;   STAGE(SB(1, 0), RB, bcol, 1);
;   STAGE(SA(1, 0), RA, brow, 1);
;   STAGE(SB(1, 1), RB, bcolB, 1);
;   WAIT_V(6);
;   BAR;
;   for (int t = 0; t < nt - 2; t += 2) {
.LBB0_130:
	s_or_b64 exec, exec, s[2:3]
	v_add_u32_e32 v149, 0x18000, v139
	v_add_u32_e32 v150, 0x1a000, v139
	v_readfirstlane_b32 s6, v149
	s_or_b32 s3, s19, 0x80
	s_mov_b32 m0, s6
	v_readfirstlane_b32 s6, v150
	v_add_u32_e32 v151, 0x8000, v139
	s_waitcnt vmcnt(4)
	s_barrier
	buffer_load_dwordx4 v138, s[68:71], s3 offen lds
	s_add_i32 s3, s3, s10
	s_mov_b32 m0, s6
	v_readfirstlane_b32 s12, v151
	v_add_u32_e32 v152, 0xa000, v139
	buffer_load_dwordx4 v138, s[68:71], s3 offen lds
	s_or_b32 s3, s17, 0x80
	s_mov_b32 s6, s70
	s_mov_b32 s7, s71
	s_mov_b32 m0, s12
	v_readfirstlane_b32 s12, v152
	v_add_u32_e32 v154, 0x1c000, v139
	buffer_load_dwordx4 v138, s[4:7], s3 offen lds
	s_add_i32 s3, s3, s10
	s_mov_b32 m0, s12
	v_readfirstlane_b32 s12, v154
	v_add_u32_e32 v156, 0x1e000, v139
	buffer_load_dwordx4 v138, s[4:7], s3 offen lds
	s_or_b32 s3, s16, 0x80
	s_mov_b32 m0, s12
	v_readfirstlane_b32 s12, v156
	buffer_load_dwordx4 v138, s[68:71], s3 offen lds
	s_add_i32 s3, s3, s10
	s_mov_b32 m0, s12
	v_and_b32_e32 v3, 15, v0
	buffer_load_dwordx4 v138, s[68:71], s3 offen lds
	v_bfe_u32 v132, v0, 4, 2
	v_lshlrev_b32_e32 v5, 4, v132
	v_lshlrev_b32_e32 v6, 6, v3
	v_lshlrev_b32_e32 v8, 2, v0
	v_or_b32_e32 v7, v5, v6
	v_and_b32_e32 v8, 32, v8
	s_mov_b32 s3, 0x10000
	v_bitop3_b32 v9, v7, s3, v8 bitop3:0xde
	s_mov_b32 s3, 0x14000
	v_bitop3_b32 v10, v7, s3, v8 bitop3:0xde
	s_mov_b32 s3, 0x18000
	v_bitop3_b32 v11, v7, s3, v8 bitop3:0xde
	s_mov_b32 s3, 0x1c000
	s_lshl_b32 s12, s22, 1
	v_bitop3_b32 v7, v7, s3, v8 bitop3:0xde
	v_lshl_or_b32 v133, v2, 6, v3
	v_lshlrev_b32_e32 v3, 13, v2
	v_lshlrev_b32_e32 v2, 6, v0
	s_add_i32 s3, s12, 0x180
	s_addk_i32 s12, 0x80
	v_bfe_u32 v131, v0, 6, 2
	v_and_b32_e32 v2, 0x3c0, v2
	s_lshl_b32 s17, s18, 1
	s_mul_i32 s19, s26, s12
	s_lshl_b32 s12, s24, 1
	s_lshr_b32 s2, s26, 6
	v_lshlrev_b32_e32 v4, 12, v131
	v_bitop3_b32 v6, v5, v8, v6 bitop3:0x36
	v_bitop3_b32 v5, v2, v8, v5 bitop3:0x36
	v_or_b32_e32 v8, 0x800, v3
	v_or_b32_e32 v12, 0x1000, v3
	v_or_b32_e32 v13, 0x1800, v3
	s_lshl_b32 s13, s26, 1
	s_add_i32 s16, s22, 0x80
	s_addk_i32 s17, 0x80
	s_addk_i32 s12, 0x80
	v_mov_b32_e32 v2, 0
	v_lshrrev_b32_e32 v130, 4, v0
	s_add_i32 s2, s2, -2
	v_add_u32_e32 v155, 0xc000, v139
	v_add_u32_e32 v153, 0xe000, v139
	s_mul_i32 s3, s26, s3
	s_mul_i32 s16, s13, s16
	s_mul_i32 s17, s26, s17
	s_mul_i32 s18, s13, s18
	s_mul_i32 s22, s13, s22
	s_mul_i32 s23, s26, s12
	s_mul_i32 s24, s13, s24
	s_mov_b32 s25, 0
	v_add_u32_e32 v158, v9, v4
	v_add_u32_e32 v137, v6, v3
	v_add_u32_e32 v136, v5, v8
	v_add_u32_e32 v135, v5, v12
	v_add_u32_e32 v134, v5, v13
	v_add_u32_e32 v157, v10, v4
	v_add_u32_e32 v146, v11, v4
	v_add_u32_e32 v140, v7, v4
	s_mov_b32 s27, 0
	v_mov_b32_e32 v3, v2
	v_mov_b32_e32 v4, v2
	v_mov_b32_e32 v5, v2
	v_mov_b32_e32 v6, v2
	v_mov_b32_e32 v7, v2
	v_mov_b32_e32 v8, v2
	v_mov_b32_e32 v9, v2
	v_mov_b32_e32 v10, v2
	v_mov_b32_e32 v11, v2
	v_mov_b32_e32 v12, v2
	v_mov_b32_e32 v13, v2
	v_mov_b32_e32 v14, v2
	v_mov_b32_e32 v15, v2
	v_mov_b32_e32 v16, v2
	v_mov_b32_e32 v17, v2
	v_mov_b32_e32 v18, v2
	v_mov_b32_e32 v19, v2
	v_mov_b32_e32 v20, v2
	v_mov_b32_e32 v21, v2
	v_mov_b32_e32 v22, v2
	v_mov_b32_e32 v23, v2
	v_mov_b32_e32 v24, v2
	v_mov_b32_e32 v25, v2
	v_mov_b32_e32 v26, v2
	v_mov_b32_e32 v27, v2
	v_mov_b32_e32 v28, v2
	v_mov_b32_e32 v29, v2
	v_mov_b32_e32 v30, v2
	v_mov_b32_e32 v31, v2
	v_mov_b32_e32 v32, v2
	v_mov_b32_e32 v33, v2
	v_mov_b32_e32 v34, v2
	v_mov_b32_e32 v35, v2
	v_mov_b32_e32 v36, v2
	v_mov_b32_e32 v37, v2
	v_mov_b32_e32 v38, v2
	v_mov_b32_e32 v39, v2
	v_mov_b32_e32 v40, v2
	v_mov_b32_e32 v41, v2
	v_mov_b32_e32 v42, v2
	v_mov_b32_e32 v43, v2
	v_mov_b32_e32 v44, v2
	v_mov_b32_e32 v45, v2
	v_mov_b32_e32 v46, v2
	v_mov_b32_e32 v47, v2
	v_mov_b32_e32 v48, v2
	v_mov_b32_e32 v49, v2
	v_mov_b32_e32 v50, v2
	v_mov_b32_e32 v51, v2
	v_mov_b32_e32 v52, v2
	v_mov_b32_e32 v53, v2
	v_mov_b32_e32 v54, v2
	v_mov_b32_e32 v55, v2
	v_mov_b32_e32 v56, v2
	v_mov_b32_e32 v57, v2
	v_mov_b32_e32 v58, v2
	v_mov_b32_e32 v59, v2
	v_mov_b32_e32 v60, v2
	v_mov_b32_e32 v61, v2
	v_mov_b32_e32 v62, v2
	v_mov_b32_e32 v63, v2
	v_mov_b32_e32 v64, v2
	v_mov_b32_e32 v65, v2
	v_mov_b32_e32 v66, v2
	v_mov_b32_e32 v67, v2
	v_mov_b32_e32 v68, v2
	v_mov_b32_e32 v69, v2
	v_mov_b32_e32 v70, v2
	v_mov_b32_e32 v71, v2
	v_mov_b32_e32 v72, v2
	v_mov_b32_e32 v73, v2
	v_mov_b32_e32 v74, v2
	v_mov_b32_e32 v75, v2
	v_mov_b32_e32 v76, v2
	v_mov_b32_e32 v77, v2
	v_mov_b32_e32 v78, v2
	v_mov_b32_e32 v79, v2
	v_mov_b32_e32 v80, v2
	v_mov_b32_e32 v81, v2
	v_mov_b32_e32 v82, v2
	v_mov_b32_e32 v83, v2
	v_mov_b32_e32 v84, v2
	v_mov_b32_e32 v85, v2
	v_mov_b32_e32 v86, v2
	v_mov_b32_e32 v87, v2
	v_mov_b32_e32 v88, v2
	v_mov_b32_e32 v89, v2
	v_mov_b32_e32 v90, v2
	v_mov_b32_e32 v91, v2
	v_mov_b32_e32 v92, v2
	v_mov_b32_e32 v93, v2
	v_mov_b32_e32 v94, v2
	v_mov_b32_e32 v95, v2
	v_mov_b32_e32 v96, v2
	v_mov_b32_e32 v97, v2
	v_mov_b32_e32 v98, v2
	v_mov_b32_e32 v99, v2
	v_mov_b32_e32 v100, v2
	v_mov_b32_e32 v101, v2
	v_mov_b32_e32 v102, v2
	v_mov_b32_e32 v103, v2
	v_mov_b32_e32 v104, v2
	v_mov_b32_e32 v105, v2
	v_mov_b32_e32 v106, v2
	v_mov_b32_e32 v107, v2
	v_mov_b32_e32 v108, v2
	v_mov_b32_e32 v109, v2
	v_mov_b32_e32 v110, v2
	v_mov_b32_e32 v111, v2
	v_mov_b32_e32 v112, v2
	v_mov_b32_e32 v113, v2
	v_mov_b32_e32 v114, v2
	v_mov_b32_e32 v115, v2
	v_mov_b32_e32 v116, v2
	v_mov_b32_e32 v117, v2
	v_mov_b32_e32 v118, v2
	v_mov_b32_e32 v119, v2
	v_mov_b32_e32 v120, v2
	v_mov_b32_e32 v121, v2
	v_mov_b32_e32 v122, v2
	v_mov_b32_e32 v123, v2
	v_mov_b32_e32 v124, v2
	v_mov_b32_e32 v125, v2
	v_mov_b32_e32 v126, v2
	v_mov_b32_e32 v127, v2
	v_mov_b32_e32 v128, v2
	v_mov_b32_e32 v129, v2
	s_waitcnt vmcnt(6)
	.p2align	6

; #define WAIT_V(n) asm volatile("s_waitcnt vmcnt(" #n ")" ::: "memory")
; #define BAR __builtin_amdgcn_s_barrier()
; template <int MODE>
; __device__ __forceinline__ void gemm_tile(const int ph, const int which, const int pm, const int pn) {
;     ...
;   STAGE(SB(0, 0), RB, bcol, 0);
;   STAGE(SA(0, 0), RA, brow, 0);
;   STAGE(SB(0, 1), RB, bcolB, 0);
;   STAGE(SA(0, 1), RA, brow + HALF, 0);
;   if (wr == 1) BAR;
;   WAIT_V(4);
;   BAR;
;   STAGE(SB(1, 0), RB, bcol, 1);
;   STAGE(SA(1, 0), RA, brow, 1);
;   STAGE(SB(1, 1), RB, bcolB, 1);
;   WAIT_V(6);
;   BAR;
;   for (int t = 0; t < nt - 2; t += 2) {
.LBB0_217:
	s_or_b64 exec, exec, s[6:7]
	v_add_u32_e32 v147, 0x18000, v136
	v_add_u32_e32 v148, 0x1a000, v136
	v_readfirstlane_b32 s7, v147
	s_or_b32 s6, s18, 0x80
	s_mov_b32 m0, s7
	v_readfirstlane_b32 s7, v148
	v_add_u32_e32 v149, 0x8000, v136
	s_waitcnt vmcnt(4)
	s_barrier
	buffer_load_dwordx4 v135, s[68:71], s6 offen lds
	s_add_i32 s6, s6, s10
	s_mov_b32 m0, s7
	s_or_b32 s13, s17, 0x80
	v_readfirstlane_b32 s17, v149
	v_add_u32_e32 v150, 0xa000, v136
	buffer_load_dwordx4 v135, s[68:71], s6 offen lds
	s_mov_b32 s6, s70
	s_mov_b32 s7, s71
	s_mov_b32 m0, s17
	v_readfirstlane_b32 s17, v150
	buffer_load_dwordx4 v135, s[4:7], s13 offen lds
	s_add_i32 s13, s13, s10
	s_mov_b32 m0, s17
	v_add_u32_e32 v152, 0x1c000, v136
	buffer_load_dwordx4 v135, s[4:7], s13 offen lds
	s_or_b32 s13, s16, 0x80
	v_readfirstlane_b32 s16, v152
	v_add_u32_e32 v154, 0x1e000, v136
	s_mov_b32 m0, s16
	v_readfirstlane_b32 s16, v154
	buffer_load_dwordx4 v135, s[68:71], s13 offen lds
	s_add_i32 s13, s13, s10
	s_mov_b32 m0, s16
	v_and_b32_e32 v3, 15, v0
	buffer_load_dwordx4 v135, s[68:71], s13 offen lds
	s_lshr_b32 s12, s28, 6
	v_and_b32_e32 v5, 48, v0
	v_lshlrev_b32_e32 v6, 6, v3
	v_lshlrev_b32_e32 v8, 2, v0
	s_add_i32 s16, s12, -2
	v_or_b32_e32 v7, v6, v5
	v_and_b32_e32 v8, 32, v8
	s_mov_b32 s12, 0x10000
	v_bitop3_b32 v9, v7, s12, v8 bitop3:0xde
	s_mov_b32 s12, 0x14000
	v_bitop3_b32 v10, v7, s12, v8 bitop3:0xde
	s_mov_b32 s12, 0x18000
	v_bitop3_b32 v11, v7, s12, v8 bitop3:0xde
	s_mov_b32 s12, 0x1c000
	v_bitop3_b32 v7, v7, s12, v8 bitop3:0xde
	s_lshl_b32 s12, s22, 1
	v_lshl_or_b32 v130, v2, 6, v3
	v_lshlrev_b32_e32 v3, 13, v2
	v_lshlrev_b32_e32 v2, 6, v0
	s_add_i32 s13, s12, 0x180
	s_addk_i32 s12, 0x80
	v_bfe_u32 v138, v0, 6, 2
	v_and_b32_e32 v2, 0x3c0, v2
	s_lshl_b32 s19, s20, 1
	s_mul_i32 s21, s28, s12
	s_lshl_b32 s12, s26, 1
	v_lshlrev_b32_e32 v4, 12, v138
	v_bitop3_b32 v6, v6, v8, v5 bitop3:0x36
	v_bitop3_b32 v5, v2, v8, v5 bitop3:0x36
	v_or_b32_e32 v8, 0x800, v3
	v_or_b32_e32 v12, 0x1000, v3
	v_or_b32_e32 v13, 0x1800, v3
	s_mul_i32 s17, s28, s13
	s_lshl_b32 s13, s28, 1
	s_add_i32 s18, s22, 0x80
	s_addk_i32 s19, 0x80
	s_addk_i32 s12, 0x80
	v_mov_b32_e32 v2, 0
	v_add_u32_e32 v153, 0xc000, v136
	v_add_u32_e32 v151, 0xe000, v136
	s_mul_i32 s18, s13, s18
	s_mul_i32 s19, s28, s19
	s_mul_i32 s20, s13, s20
	s_mul_i32 s22, s13, s22
	s_mul_i32 s25, s28, s12
	s_mul_i32 s26, s13, s26
	s_mov_b32 s27, 0
	v_add_u32_e32 v156, v9, v4
	v_add_u32_e32 v134, v6, v3
	v_add_u32_e32 v133, v5, v8
	v_add_u32_e32 v132, v5, v12
	v_add_u32_e32 v131, v5, v13
	v_add_u32_e32 v155, v10, v4
	v_add_u32_e32 v144, v11, v4
	v_add_u32_e32 v137, v7, v4
	s_mov_b32 vcc_lo, 0
	v_mov_b32_e32 v3, v2
	v_mov_b32_e32 v4, v2
	v_mov_b32_e32 v5, v2
	v_mov_b32_e32 v6, v2
	v_mov_b32_e32 v7, v2
	v_mov_b32_e32 v8, v2
	v_mov_b32_e32 v9, v2
	v_mov_b32_e32 v10, v2
	v_mov_b32_e32 v11, v2
	v_mov_b32_e32 v12, v2
	v_mov_b32_e32 v13, v2
	v_mov_b32_e32 v14, v2
	v_mov_b32_e32 v15, v2
	v_mov_b32_e32 v16, v2
	v_mov_b32_e32 v17, v2
	v_mov_b32_e32 v18, v2
	v_mov_b32_e32 v19, v2
	v_mov_b32_e32 v20, v2
	v_mov_b32_e32 v21, v2
	v_mov_b32_e32 v22, v2
	v_mov_b32_e32 v23, v2
	v_mov_b32_e32 v24, v2
	v_mov_b32_e32 v25, v2
	v_mov_b32_e32 v26, v2
	v_mov_b32_e32 v27, v2
	v_mov_b32_e32 v28, v2
	v_mov_b32_e32 v29, v2
	v_mov_b32_e32 v30, v2
	v_mov_b32_e32 v31, v2
	v_mov_b32_e32 v32, v2
	v_mov_b32_e32 v33, v2
	v_mov_b32_e32 v34, v2
	v_mov_b32_e32 v35, v2
	v_mov_b32_e32 v36, v2
	v_mov_b32_e32 v37, v2
	v_mov_b32_e32 v38, v2
	v_mov_b32_e32 v39, v2
	v_mov_b32_e32 v40, v2
	v_mov_b32_e32 v41, v2
	v_mov_b32_e32 v42, v2
	v_mov_b32_e32 v43, v2
	v_mov_b32_e32 v44, v2
	v_mov_b32_e32 v45, v2
	v_mov_b32_e32 v46, v2
	v_mov_b32_e32 v47, v2
	v_mov_b32_e32 v48, v2
	v_mov_b32_e32 v49, v2
	v_mov_b32_e32 v50, v2
	v_mov_b32_e32 v51, v2
	v_mov_b32_e32 v52, v2
	v_mov_b32_e32 v53, v2
	v_mov_b32_e32 v54, v2
	v_mov_b32_e32 v55, v2
	v_mov_b32_e32 v56, v2
	v_mov_b32_e32 v57, v2
	v_mov_b32_e32 v58, v2
	v_mov_b32_e32 v59, v2
	v_mov_b32_e32 v60, v2
	v_mov_b32_e32 v61, v2
	v_mov_b32_e32 v62, v2
	v_mov_b32_e32 v63, v2
	v_mov_b32_e32 v64, v2
	v_mov_b32_e32 v65, v2
	v_mov_b32_e32 v66, v2
	v_mov_b32_e32 v67, v2
	v_mov_b32_e32 v68, v2
	v_mov_b32_e32 v69, v2
	v_mov_b32_e32 v70, v2
	v_mov_b32_e32 v71, v2
	v_mov_b32_e32 v72, v2
	v_mov_b32_e32 v73, v2
	v_mov_b32_e32 v74, v2
	v_mov_b32_e32 v75, v2
	v_mov_b32_e32 v76, v2
	v_mov_b32_e32 v77, v2
	v_mov_b32_e32 v78, v2
	v_mov_b32_e32 v79, v2
	v_mov_b32_e32 v80, v2
	v_mov_b32_e32 v81, v2
	v_mov_b32_e32 v82, v2
	v_mov_b32_e32 v83, v2
	v_mov_b32_e32 v84, v2
	v_mov_b32_e32 v85, v2
	v_mov_b32_e32 v86, v2
	v_mov_b32_e32 v87, v2
	v_mov_b32_e32 v88, v2
	v_mov_b32_e32 v89, v2
	v_mov_b32_e32 v90, v2
	v_mov_b32_e32 v91, v2
	v_mov_b32_e32 v92, v2
	v_mov_b32_e32 v93, v2
	v_mov_b32_e32 v94, v2
	v_mov_b32_e32 v95, v2
	v_mov_b32_e32 v96, v2
	v_mov_b32_e32 v97, v2
	v_mov_b32_e32 v98, v2
	v_mov_b32_e32 v99, v2
	v_mov_b32_e32 v100, v2
	v_mov_b32_e32 v101, v2
	v_mov_b32_e32 v102, v2
	v_mov_b32_e32 v103, v2
	v_mov_b32_e32 v104, v2
	v_mov_b32_e32 v105, v2
	v_mov_b32_e32 v106, v2
	v_mov_b32_e32 v107, v2
	v_mov_b32_e32 v108, v2
	v_mov_b32_e32 v109, v2
	v_mov_b32_e32 v110, v2
	v_mov_b32_e32 v111, v2
	v_mov_b32_e32 v112, v2
	v_mov_b32_e32 v113, v2
	v_mov_b32_e32 v114, v2
	v_mov_b32_e32 v115, v2
	v_mov_b32_e32 v116, v2
	v_mov_b32_e32 v117, v2
	v_mov_b32_e32 v118, v2
	v_mov_b32_e32 v119, v2
	v_mov_b32_e32 v120, v2
	v_mov_b32_e32 v121, v2
	v_mov_b32_e32 v122, v2
	v_mov_b32_e32 v123, v2
	v_mov_b32_e32 v124, v2
	v_mov_b32_e32 v125, v2
	v_mov_b32_e32 v126, v2
	v_mov_b32_e32 v127, v2
	v_mov_b32_e32 v128, v2
	v_mov_b32_e32 v129, v2
	s_waitcnt vmcnt(6)
	.p2align	6

; #define WAIT_V(n) asm volatile("s_waitcnt vmcnt(" #n ")" ::: "memory")
; #define BAR __builtin_amdgcn_s_barrier()
; template <int MODE>
; __device__ __forceinline__ void gemm_tile(const int ph, const int which, const int pm, const int pn) {
;     ...
;   STAGE(SB(0, 0), RB, bcol, 0);
;   STAGE(SA(0, 0), RA, brow, 0);
;   STAGE(SB(0, 1), RB, bcolB, 0);
;   STAGE(SA(0, 1), RA, brow + HALF, 0);
;   if (wr == 1) BAR;
;   WAIT_V(4);
;   BAR;
;   STAGE(SB(1, 0), RB, bcol, 1);
;   STAGE(SA(1, 0), RA, brow, 1);
;   STAGE(SB(1, 1), RB, bcolB, 1);
;   WAIT_V(6);
;   BAR;
;   for (int t = 0; t < nt - 2; t += 2) {
.LBB0_369:
	s_or_b64 exec, exec, s[2:3]
	v_add_u32_e32 v145, 0x18000, v131
	v_add_u32_e32 v146, 0x1a000, v131
	v_readfirstlane_b32 s6, v145
	s_or_b32 s3, s17, 0x80
	s_mov_b32 m0, s6
	v_readfirstlane_b32 s6, v146
	s_waitcnt vmcnt(4)
	s_barrier
	buffer_load_dwordx4 v130, s[68:71], s3 offen lds
	s_add_i32 s3, s3, s8
	s_mov_b32 m0, s6
	v_add_u32_e32 v147, 0x8000, v131
	buffer_load_dwordx4 v130, s[68:71], s3 offen lds
	s_or_b32 s3, s11, 0x80
	v_readfirstlane_b32 s11, v147
	v_add_u32_e32 v148, 0xa000, v131
	s_mov_b32 s6, s70
	s_mov_b32 s7, s71
	s_mov_b32 m0, s11
	v_readfirstlane_b32 s11, v148
	buffer_load_dwordx4 v130, s[4:7], s3 offen lds
	s_add_i32 s3, s3, s8
	s_mov_b32 m0, s11
	v_add_u32_e32 v150, 0x1c000, v131
	buffer_load_dwordx4 v130, s[4:7], s3 offen lds
	s_or_b32 s3, s10, 0x80
	v_readfirstlane_b32 s10, v150
	v_add_u32_e32 v152, 0x1e000, v131
	s_mov_b32 m0, s10
	v_readfirstlane_b32 s10, v152
	buffer_load_dwordx4 v130, s[68:71], s3 offen lds
	s_add_i32 s3, s3, s8
	s_mov_b32 m0, s10
	v_and_b32_e32 v2, 15, v164
	buffer_load_dwordx4 v130, s[68:71], s3 offen lds
	v_bfe_u32 v162, v164, 4, 2
	v_lshlrev_b32_e32 v4, 4, v162
	v_lshlrev_b32_e32 v5, 6, v2
	v_lshlrev_b32_e32 v7, 2, v164
	v_or_b32_e32 v6, v4, v5
	v_and_b32_e32 v7, 32, v7
	s_mov_b32 s3, 0x10000
	v_bitop3_b32 v8, v6, s3, v7 bitop3:0xde
	s_mov_b32 s3, 0x14000
	v_bitop3_b32 v9, v6, s3, v7 bitop3:0xde
	s_mov_b32 s3, 0x18000
	v_bitop3_b32 v10, v6, s3, v7 bitop3:0xde
	s_mov_b32 s3, 0x1c000
	s_lshl_b32 s12, s18, 1
	v_bitop3_b32 v6, v6, s3, v7 bitop3:0xde
	v_lshl_or_b32 v163, v167, 6, v2
	v_lshlrev_b32_e32 v2, 6, v164
	s_add_i32 s3, s12, 0x180
	s_addk_i32 s12, 0x80
	v_bfe_u32 v0, v164, 6, 2
	v_lshlrev_b32_e32 v11, 13, v167
	v_and_b32_e32 v2, 0x3c0, v2
	s_lshl_b32 s11, s16, 1
	s_mul_i32 s17, s26, s12
	s_lshl_b32 s12, s20, 1
	s_lshr_b32 s2, s26, 6
	v_lshlrev_b32_e32 v3, 12, v0
	v_bitop3_b32 v5, v4, v7, v5 bitop3:0x36
	v_bitop3_b32 v4, v2, v7, v4 bitop3:0x36
	v_or_b32_e32 v7, 0x800, v11
	v_or_b32_e32 v12, 0x1000, v11
	v_or_b32_e32 v13, 0x1800, v11
	s_lshl_b32 s13, s26, 1
	s_add_i32 s10, s18, 0x80
	s_addk_i32 s11, 0x80
	s_addk_i32 s12, 0x80
	v_mov_b32_e32 v2, 0
	s_add_i32 s2, s2, -2
	v_add_u32_e32 v151, 0xc000, v131
	v_add_u32_e32 v149, 0xe000, v131
	s_mul_i32 s3, s26, s3
	s_mul_i32 s10, s13, s10
	s_mul_i32 s11, s26, s11
	s_mul_i32 s16, s13, s16
	s_mul_i32 s18, s13, s18
	s_mul_i32 s19, s26, s12
	s_mul_i32 s20, s13, s20
	s_mov_b32 s21, 0
	v_add_u32_e32 v154, v8, v3
	v_add_u32_e32 v141, v5, v11
	v_add_u32_e32 v140, v4, v7
	v_add_u32_e32 v139, v4, v12
	v_add_u32_e32 v138, v4, v13
	v_add_u32_e32 v153, v9, v3
	v_add_u32_e32 v137, v10, v3
	v_add_u32_e32 v142, v6, v3
	s_mov_b32 s22, 0
	v_mov_b32_e32 v3, v2
	v_mov_b32_e32 v4, v2
	v_mov_b32_e32 v5, v2
	v_mov_b32_e32 v6, v2
	v_mov_b32_e32 v7, v2
	v_mov_b32_e32 v8, v2
	v_mov_b32_e32 v9, v2
	v_mov_b32_e32 v18, v2
	v_mov_b32_e32 v19, v2
	v_mov_b32_e32 v20, v2
	v_mov_b32_e32 v21, v2
	v_mov_b32_e32 v30, v2
	v_mov_b32_e32 v31, v2
	v_mov_b32_e32 v32, v2
	v_mov_b32_e32 v33, v2
	v_mov_b32_e32 v42, v2
	v_mov_b32_e32 v43, v2
	v_mov_b32_e32 v44, v2
	v_mov_b32_e32 v45, v2
	v_mov_b32_e32 v54, v2
	v_mov_b32_e32 v55, v2
	v_mov_b32_e32 v56, v2
	v_mov_b32_e32 v57, v2
	v_mov_b32_e32 v66, v2
	v_mov_b32_e32 v67, v2
	v_mov_b32_e32 v68, v2
	v_mov_b32_e32 v69, v2
	v_mov_b32_e32 v78, v2
	v_mov_b32_e32 v79, v2
	v_mov_b32_e32 v80, v2
	v_mov_b32_e32 v81, v2
	v_mov_b32_e32 v10, v2
	v_mov_b32_e32 v11, v2
	v_mov_b32_e32 v12, v2
	v_mov_b32_e32 v13, v2
	v_mov_b32_e32 v22, v2
	v_mov_b32_e32 v23, v2
	v_mov_b32_e32 v24, v2
	v_mov_b32_e32 v25, v2
	v_mov_b32_e32 v34, v2
	v_mov_b32_e32 v35, v2
	v_mov_b32_e32 v36, v2
	v_mov_b32_e32 v37, v2
	v_mov_b32_e32 v46, v2
	v_mov_b32_e32 v47, v2
	v_mov_b32_e32 v48, v2
	v_mov_b32_e32 v49, v2
	v_mov_b32_e32 v58, v2
	v_mov_b32_e32 v59, v2
	v_mov_b32_e32 v60, v2
	v_mov_b32_e32 v61, v2
	v_mov_b32_e32 v70, v2
	v_mov_b32_e32 v71, v2
	v_mov_b32_e32 v72, v2
	v_mov_b32_e32 v73, v2
	v_mov_b32_e32 v82, v2
	v_mov_b32_e32 v83, v2
	v_mov_b32_e32 v84, v2
	v_mov_b32_e32 v85, v2
	v_mov_b32_e32 v94, v2
	v_mov_b32_e32 v95, v2
	v_mov_b32_e32 v96, v2
	v_mov_b32_e32 v97, v2
	v_mov_b32_e32 v14, v2
	v_mov_b32_e32 v15, v2
	v_mov_b32_e32 v16, v2
	v_mov_b32_e32 v17, v2
	v_mov_b32_e32 v26, v2
	v_mov_b32_e32 v27, v2
	v_mov_b32_e32 v28, v2
	v_mov_b32_e32 v29, v2
	v_mov_b32_e32 v38, v2
	v_mov_b32_e32 v39, v2
	v_mov_b32_e32 v40, v2
	v_mov_b32_e32 v41, v2
	v_mov_b32_e32 v50, v2
	v_mov_b32_e32 v51, v2
	v_mov_b32_e32 v52, v2
	v_mov_b32_e32 v53, v2
	v_mov_b32_e32 v62, v2
	v_mov_b32_e32 v63, v2
	v_mov_b32_e32 v64, v2
	v_mov_b32_e32 v65, v2
	v_mov_b32_e32 v74, v2
	v_mov_b32_e32 v75, v2
	v_mov_b32_e32 v76, v2
	v_mov_b32_e32 v77, v2
	v_mov_b32_e32 v86, v2
	v_mov_b32_e32 v87, v2
	v_mov_b32_e32 v88, v2
	v_mov_b32_e32 v89, v2
	v_mov_b32_e32 v98, v2
	v_mov_b32_e32 v99, v2
	v_mov_b32_e32 v100, v2
	v_mov_b32_e32 v101, v2
	v_mov_b32_e32 v90, v2
	v_mov_b32_e32 v91, v2
	v_mov_b32_e32 v92, v2
	v_mov_b32_e32 v93, v2
	v_mov_b32_e32 v102, v2
	v_mov_b32_e32 v103, v2
	v_mov_b32_e32 v104, v2
	v_mov_b32_e32 v105, v2
	v_mov_b32_e32 v106, v2
	v_mov_b32_e32 v107, v2
	v_mov_b32_e32 v108, v2
	v_mov_b32_e32 v109, v2
	v_mov_b32_e32 v110, v2
	v_mov_b32_e32 v111, v2
	v_mov_b32_e32 v112, v2
	v_mov_b32_e32 v113, v2
	v_mov_b32_e32 v114, v2
	v_mov_b32_e32 v115, v2
	v_mov_b32_e32 v116, v2
	v_mov_b32_e32 v117, v2
	v_mov_b32_e32 v118, v2
	v_mov_b32_e32 v119, v2
	v_mov_b32_e32 v120, v2
	v_mov_b32_e32 v121, v2
	v_mov_b32_e32 v122, v2
	v_mov_b32_e32 v123, v2
	v_mov_b32_e32 v124, v2
	v_mov_b32_e32 v125, v2
	v_mov_b32_e32 v126, v2
	v_mov_b32_e32 v127, v2
	v_mov_b32_e32 v128, v2
	v_mov_b32_e32 v129, v2
	s_waitcnt vmcnt(6)
	.p2align	6

; #define WAIT_V(n) asm volatile("s_waitcnt vmcnt(" #n ")" ::: "memory")
; #define BAR __builtin_amdgcn_s_barrier()
; template <int MODE>
; __device__ __forceinline__ void gemm_tile(const int ph, const int which, const int pm, const int pn) {
;     ...
;   f32x4 acc[2][2][4][2] = {};
;   bf16x8 At[4][2], B0[2][2], B1[2][2];
;   const int nt = K / BK;
;   const int brow = browA;
;   STAGE(SB(0, 0), RB, bcol, 0);
;   STAGE(SA(0, 0), RA, brow, 0);
;   STAGE(SB(0, 1), RB, bcolB, 0);
;   STAGE(SA(0, 1), RA, brow + HALF, 0);
;   if (wr == 1) BAR;
;   WAIT_V(4);
;   BAR;
;   STAGE(SB(1, 0), RB, bcol, 1);
;   STAGE(SA(1, 0), RA, brow, 1);
;   STAGE(SB(1, 1), RB, bcolB, 1);
;   WAIT_V(6);
;   BAR;
.LBB0_539:
	s_or_b64 exec, exec, s[2:3]
	v_add_u32_e32 v147, 0x18000, v137
	v_add_u32_e32 v148, 0x1a000, v137
	v_readfirstlane_b32 s6, v147
	s_or_b32 s3, s19, 0x80
	s_mov_b32 m0, s6
	v_readfirstlane_b32 s6, v148
	s_waitcnt vmcnt(4)
	s_barrier
	buffer_load_dwordx4 v136, s[68:71], s3 offen lds
	s_add_i32 s3, s3, s8
	s_mov_b32 m0, s6
	v_add_u32_e32 v149, 0x8000, v137
	buffer_load_dwordx4 v136, s[68:71], s3 offen lds
	s_or_b32 s3, s11, 0x80
	v_readfirstlane_b32 s11, v149
	v_add_u32_e32 v150, 0xa000, v137
	s_mov_b32 s6, s70
	s_mov_b32 s7, s71
	s_mov_b32 m0, s11
	v_readfirstlane_b32 s11, v150
	buffer_load_dwordx4 v136, s[4:7], s3 offen lds
	s_add_i32 s3, s3, s8
	s_mov_b32 m0, s11
	v_add_u32_e32 v152, 0x1c000, v137
	buffer_load_dwordx4 v136, s[4:7], s3 offen lds
	s_or_b32 s3, s10, 0x80
	v_readfirstlane_b32 s10, v152
	v_add_u32_e32 v154, 0x1e000, v137
	s_mov_b32 m0, s10
	v_readfirstlane_b32 s10, v154
	buffer_load_dwordx4 v136, s[68:71], s3 offen lds
	s_add_i32 s3, s3, s8
	s_mov_b32 m0, s10
	v_and_b32_e32 v3, 15, v0
	buffer_load_dwordx4 v136, s[68:71], s3 offen lds
	v_and_b32_e32 v5, 48, v0
	v_lshlrev_b32_e32 v6, 6, v3
	v_lshlrev_b32_e32 v8, 2, v0
	v_or_b32_e32 v7, v6, v5
	v_and_b32_e32 v8, 32, v8
	s_mov_b32 s3, 0x10000
	v_bitop3_b32 v9, v7, s3, v8 bitop3:0xde
	s_mov_b32 s3, 0x14000
	v_bitop3_b32 v10, v7, s3, v8 bitop3:0xde
	s_mov_b32 s3, 0x18000
	v_lshl_or_b32 v131, v2, 6, v3
	v_lshlrev_b32_e32 v3, 13, v2
	v_lshlrev_b32_e32 v2, 6, v0
	v_bfe_u32 v130, v0, 6, 2
	v_bitop3_b32 v11, v7, s3, v8 bitop3:0xde
	s_mov_b32 s3, 0x1c000
	v_and_b32_e32 v2, 0x3c0, v2
	s_lshl_b32 s19, s20, 1
	s_lshl_b32 s11, s17, 1
	s_lshl_b32 s21, s22, 1
	s_lshr_b32 s2, s24, 6
	v_lshlrev_b32_e32 v4, 12, v130
	v_bitop3_b32 v6, v6, v8, v5 bitop3:0x36
	v_bitop3_b32 v7, v7, s3, v8 bitop3:0xde
	v_bitop3_b32 v5, v2, v8, v5 bitop3:0x36
	v_or_b32_e32 v8, 0x800, v3
	v_or_b32_e32 v12, 0x1000, v3
	v_or_b32_e32 v13, 0x1800, v3
	s_add_i32 s3, s19, 0x180
	s_lshl_b32 s23, s24, 1
	s_add_i32 s10, s20, 0x80
	s_addk_i32 s11, 0x80
	s_addk_i32 s19, 0x80
	s_addk_i32 s21, 0x80
	v_mov_b32_e32 v2, 0
	s_add_i32 s2, s2, -2
	v_add_u32_e32 v153, 0xc000, v137
	v_add_u32_e32 v151, 0xe000, v137
	s_mul_i32 s3, s24, s3
	s_mul_i32 s10, s23, s10
	s_mul_i32 s11, s24, s11
	s_mul_i32 s17, s23, s17
	s_mul_i32 s19, s24, s19
	s_mul_i32 s20, s23, s20
	s_mul_i32 s21, s24, s21
	s_mul_i32 s22, s23, s22
	s_mov_b32 s23, 0
	v_add_u32_e32 v156, v9, v4
	v_add_u32_e32 v135, v6, v3
	v_add_u32_e32 v134, v5, v8
	v_add_u32_e32 v133, v5, v12
	v_add_u32_e32 v132, v5, v13
	v_add_u32_e32 v155, v10, v4
	v_add_u32_e32 v144, v11, v4
	v_add_u32_e32 v138, v7, v4
	s_mov_b32 s25, 0
	v_mov_b32_e32 v3, v2
	v_mov_b32_e32 v4, v2
	v_mov_b32_e32 v5, v2
	v_mov_b32_e32 v6, v2
	v_mov_b32_e32 v7, v2
	v_mov_b32_e32 v8, v2
	v_mov_b32_e32 v9, v2
	v_mov_b32_e32 v10, v2
	v_mov_b32_e32 v11, v2
	v_mov_b32_e32 v12, v2
	v_mov_b32_e32 v13, v2
	v_mov_b32_e32 v14, v2
	v_mov_b32_e32 v15, v2
	v_mov_b32_e32 v16, v2
	v_mov_b32_e32 v17, v2
	v_mov_b32_e32 v18, v2
	v_mov_b32_e32 v19, v2
	v_mov_b32_e32 v20, v2
	v_mov_b32_e32 v21, v2
	v_mov_b32_e32 v22, v2
	v_mov_b32_e32 v23, v2
	v_mov_b32_e32 v24, v2
	v_mov_b32_e32 v25, v2
	s_waitcnt vmcnt(18)
	v_mov_b32_e32 v26, v2
	v_mov_b32_e32 v27, v2
	v_mov_b32_e32 v28, v2
	v_mov_b32_e32 v29, v2
	s_waitcnt vmcnt(16)
	v_mov_b32_e32 v30, v2
	v_mov_b32_e32 v31, v2
	v_mov_b32_e32 v32, v2
	v_mov_b32_e32 v33, v2
	s_waitcnt vmcnt(14)
	v_mov_b32_e32 v34, v2
	v_mov_b32_e32 v35, v2
	v_mov_b32_e32 v36, v2
	v_mov_b32_e32 v37, v2
	v_mov_b32_e32 v38, v2
	v_mov_b32_e32 v39, v2
	v_mov_b32_e32 v40, v2
	v_mov_b32_e32 v41, v2
	v_mov_b32_e32 v42, v2
	v_mov_b32_e32 v43, v2
	v_mov_b32_e32 v44, v2
	v_mov_b32_e32 v45, v2
	v_mov_b32_e32 v46, v2
	v_mov_b32_e32 v47, v2
	v_mov_b32_e32 v48, v2
	v_mov_b32_e32 v49, v2
	v_mov_b32_e32 v50, v2
	v_mov_b32_e32 v51, v2
	v_mov_b32_e32 v52, v2
	v_mov_b32_e32 v53, v2
	v_mov_b32_e32 v54, v2
	v_mov_b32_e32 v55, v2
	v_mov_b32_e32 v56, v2
	v_mov_b32_e32 v57, v2
	v_mov_b32_e32 v58, v2
	v_mov_b32_e32 v59, v2
	v_mov_b32_e32 v60, v2
	v_mov_b32_e32 v61, v2
	v_mov_b32_e32 v62, v2
	v_mov_b32_e32 v63, v2
	v_mov_b32_e32 v64, v2
	v_mov_b32_e32 v65, v2
	v_mov_b32_e32 v66, v2
	v_mov_b32_e32 v67, v2
	v_mov_b32_e32 v68, v2
	v_mov_b32_e32 v69, v2
	v_mov_b32_e32 v70, v2
	v_mov_b32_e32 v71, v2
	v_mov_b32_e32 v72, v2
	v_mov_b32_e32 v73, v2
	v_mov_b32_e32 v74, v2
	v_mov_b32_e32 v75, v2
	v_mov_b32_e32 v76, v2
	v_mov_b32_e32 v77, v2
	v_mov_b32_e32 v78, v2
	v_mov_b32_e32 v79, v2
	v_mov_b32_e32 v80, v2
	v_mov_b32_e32 v81, v2
	v_mov_b32_e32 v82, v2
	v_mov_b32_e32 v83, v2
	v_mov_b32_e32 v84, v2
	v_mov_b32_e32 v85, v2
	v_mov_b32_e32 v86, v2
	v_mov_b32_e32 v87, v2
	v_mov_b32_e32 v88, v2
	v_mov_b32_e32 v89, v2
	v_mov_b32_e32 v90, v2
	v_mov_b32_e32 v91, v2
	v_mov_b32_e32 v92, v2
	v_mov_b32_e32 v93, v2
	v_mov_b32_e32 v94, v2
	v_mov_b32_e32 v95, v2
	v_mov_b32_e32 v96, v2
	v_mov_b32_e32 v97, v2
	v_mov_b32_e32 v98, v2
	v_mov_b32_e32 v99, v2
	v_mov_b32_e32 v100, v2
	v_mov_b32_e32 v101, v2
	v_mov_b32_e32 v102, v2
	v_mov_b32_e32 v103, v2
	v_mov_b32_e32 v104, v2
	v_mov_b32_e32 v105, v2
	v_mov_b32_e32 v106, v2
	v_mov_b32_e32 v107, v2
	v_mov_b32_e32 v108, v2
	v_mov_b32_e32 v109, v2
	v_mov_b32_e32 v110, v2
	v_mov_b32_e32 v111, v2
	v_mov_b32_e32 v112, v2
	v_mov_b32_e32 v113, v2
	v_mov_b32_e32 v114, v2
	v_mov_b32_e32 v115, v2
	v_mov_b32_e32 v116, v2
	v_mov_b32_e32 v117, v2
	v_mov_b32_e32 v118, v2
	v_mov_b32_e32 v119, v2
	v_mov_b32_e32 v120, v2
	v_mov_b32_e32 v121, v2
	v_mov_b32_e32 v122, v2
	v_mov_b32_e32 v123, v2
	v_mov_b32_e32 v124, v2
	v_mov_b32_e32 v125, v2
	v_mov_b32_e32 v126, v2
	v_mov_b32_e32 v127, v2
	v_mov_b32_e32 v128, v2
	v_mov_b32_e32 v129, v2
	s_waitcnt vmcnt(6)
	.p2align	6

; template <int LSEL>
; __device__ __forceinline__ void hy_conv(const bf16_t* Z, const bf16_t* G, f32x4 (&acc)[4][4], int w, int lane) {
;     ...
;   for (int d = i_lo - (NB - 1); d <= i_hi; ++d) {
;     bf16x8 bf[4][2];
; #pragma unroll
;     for (int k = 0; k < 4; ++k) {
;       int js = (q0 + k) * BPT - d;
;       js = min(max(js, LSEL ? -1 : 0), NB - 1);
;       const bf16_t* bp = Z + zb + 64 * js;
;       bf[k][0] = *(const bf16x8*)bp;
;       bf[k][1] = *(const bf16x8*)(bp + 32);
;     }
;     const bf16_t* gb = G + (L - 64 * d + 8 * quad - r - s);
.LBB0_834:
	s_addk_i32 s9, 0xff80
	s_add_i32 s8, s8, -1
	s_cmpk_lg_i32 s9, 0xee80
	s_cbranch_scc0 .LBB0_843
	.p2align	6

; template <int LSEL>
; __device__ __forceinline__ void hy_conv(const bf16_t* Z, const bf16_t* G, f32x4 (&acc)[4][4], int w, int lane) {
;     ...
;   for (int d = i_lo - (NB - 1); d <= i_hi; ++d) {
;     bf16x8 bf[4][2];
; #pragma unroll
;     for (int k = 0; k < 4; ++k) {
;       int js = (q0 + k) * BPT - d;
;       js = min(max(js, LSEL ? -1 : 0), NB - 1);
;       const bf16_t* bp = Z + zb + 64 * js;
;       bf[k][0] = *(const bf16x8*)bp;
;       bf[k][1] = *(const bf16x8*)(bp + 32);
;     }
;     const bf16_t* gb = G + (L - 64 * d + 8 * quad - r - s);
.LBB0_927:
	s_addk_i32 s8, 0xff80
	s_add_i32 s9, s9, -1
	s_cmpk_lg_i32 s8, 0xee80
	s_cbranch_scc0 .LBB0_936
	.p2align	6

; template <int LSEL>
; __device__ __forceinline__ void hy_conv(const bf16_t* Z, const bf16_t* G, f32x4 (&acc)[4][4], int w, int lane) {
;     ...
;   for (int d = i_lo - (NB - 1); d <= i_hi; ++d) {
;     bf16x8 bf[4][2];
; #pragma unroll
;     for (int k = 0; k < 4; ++k) {
;       int js = (q0 + k) * BPT - d;
;       js = min(max(js, LSEL ? -1 : 0), NB - 1);
;       const bf16_t* bp = Z + zb + 64 * js;
;       bf[k][0] = *(const bf16x8*)bp;
;       bf[k][1] = *(const bf16x8*)(bp + 32);
;     }
;     const bf16_t* gb = G + (L - 64 * d + 8 * quad - r - s);
.LBB0_1111:
	s_add_i32 s9, s9, -1
	s_addk_i32 s8, 0xff80
	s_cmpk_lg_i32 s8, 0xdc80
	s_cbranch_scc0 .LBB0_1120
	.p2align	6

; template <int LSEL>
; __device__ __forceinline__ void hy_conv(const bf16_t* Z, const bf16_t* G, f32x4 (&acc)[4][4], int w, int lane) {
;     ...
;   for (int d = i_lo - (NB - 1); d <= i_hi; ++d) {
;     bf16x8 bf[4][2];
; #pragma unroll
;     for (int k = 0; k < 4; ++k) {
;       int js = (q0 + k) * BPT - d;
;       js = min(max(js, LSEL ? -1 : 0), NB - 1);
;       const bf16_t* bp = Z + zb + 64 * js;
;       bf[k][0] = *(const bf16x8*)bp;
;       bf[k][1] = *(const bf16x8*)(bp + 32);
;     }
;     const bf16_t* gb = G + (L - 64 * d + 8 * quad - r - s);
.LBB0_1204:
	s_add_i32 s8, s8, -1
	s_addk_i32 s9, 0xff80
	s_cmpk_lg_i32 s9, 0xdc80
	s_cbranch_scc0 .LBB0_1213
	.p2align	6
